# v66 + P2 V^T units: next unit's loads issued one unit ahead into spare registers
# speedup vs baseline: 1.3223x; 1.0065x over previous
; __device__ __forceinline__ void vt_unit(const Params& p, int unit, bfu* tile  ) {
;     const int blk = unit & 15, bh = unit >> 4, h = bh & 15, b = bh >> 4, t0 = blk * 256, tid = threadIdx.x;
;     const bfu* proj = (const bfu*)(p.ws + WS_PROJ);
;     bfu* vt = (bfu*)(p.ws + WS_VT);
; #pragma unroll
;     for (int i = 0; i < 4; ++i) {
;         const int e = tid + 512 * i, t = e >> 3, d8 = (e & 7) * 8;
;         const uint4 v = *(const uint4*)(proj + (size_t)(b * 4096 + t0 + t) * NPROJ + 2048 + h * 64 + d8);
; __device__ __forceinline__ void phase2(const Params& p, unsigned char* lds, int bid, int G) {
;     constexpr int U_CP = 0, U_CS = 32, U_VT = 1024, U_DT = 130, NU = U_CP + U_CS + U_VT + U_DT;
;     const int tid = threadIdx.x;
;     for (int u = bid; u < NU; u += G) {
;         int j = u;
;         if (j < U_VT) { vt_unit(p, j, (bfu*)lds); continue; }
.LBB0_236:
	s_or_b64 exec, exec, s[0:1]
	v_readlane_b32 s0, v252, 1
	v_bfe_u32 v175, v172, 4, 2
	v_readlane_b32 s1, v252, 2
	s_cmpk_gt_i32 s2, 0x4a1
	v_lshrrev_b32_e32 v194, 6, v172
	v_and_b32_e32 v174, 15, v172
	v_lshlrev_b32_e32 v181, 3, v172
	v_lshrrev_b32_e32 v76, 3, v172
	v_lshlrev_b32_e32 v176, 4, v175
	s_waitcnt lgkmcnt(0)
	s_barrier
	s_cbranch_scc1 .LBB0_279
	s_movk_i32 s3, 0xff
	v_cmp_lt_u32_e64 s[10:11], s3, v172
	v_and_b32_e32 v0, 56, v181
	s_movk_i32 s3, 0x214
	v_add_u32_e32 v3, 0x200, v172
	v_or_b32_e32 v4, 0x400, v172
	v_add_u32_e32 v5, 0x600, v172
	v_mad_u32_u24 v1, v0, s3, 0
	v_lshrrev_b32_e32 v100, 3, v3
	v_lshrrev_b32_e32 v102, 3, v4
	v_lshrrev_b32_e32 v104, 3, v5
	v_lshl_add_u32 v99, v76, 1, v1
	v_lshl_add_u32 v101, v100, 1, v1
	v_lshl_add_u32 v103, v102, 1, v1
	v_lshl_add_u32 v105, v104, 1, v1
	v_and_b32_e32 v1, 31, v172
	v_lshlrev_b32_e32 v2, 3, v1
	v_lshl_add_u32 v108, v1, 4, 0
	v_bfe_u32 v1, v172, 3, 2
	v_lshrrev_b32_e32 v109, 5, v3
	v_lshrrev_b32_e32 v111, 5, v4
	v_lshlrev_b32_e32 v3, 1, v1
	v_lshlrev_b32_e32 v4, 3, v0
	v_and_b32_e32 v6, 8, v181
	v_add3_u32 v115, 0, v3, v4
	v_lshlrev_b32_e32 v4, 10, v1
	v_and_b32_e32 v1, 30, v172
	v_lshlrev_b32_e32 v3, 5, v6
	v_add3_u32 v116, 0, v1, v3
	v_lshlrev_b32_e32 v1, 7, v172
	v_and_b32_e32 v8, 0xf00, v1
	v_lshlrev_b32_e32 v1, 14, v194
	v_lshl_add_u32 v1, s2, 17, v1
	v_mov_b32_e32 v65, 0
	v_and_b32_e32 v77, 12, v194
	v_lshrrev_b32_e32 v106, 5, v172
	v_lshrrev_b32_e32 v113, 5, v5
	v_lshlrev_b32_e32 v68, 4, v175
	v_lshl_or_b32 v1, v174, 10, v1
	v_or_b32_e32 v67, 0xffffdf00, v194
	v_and_b32_e32 v66, 0x7f8, v181
	s_mov_b32 s5, 0
	v_cmp_ne_u32_e64 s[6:7], 0, v77
	v_cmp_lt_u32_e64 s[8:9], 4, v77
	v_add_u32_e32 v92, -5, v77
	v_or_b32_e32 v93, 1, v77
	v_add_u32_e32 v94, -4, v77
	v_or_b32_e32 v95, 2, v77
	v_add_u32_e32 v96, -3, v77
	v_or_b32_e32 v97, 3, v194
	v_add_u32_e32 v98, -2, v77
	v_mul_u32_u24_e32 v107, 0x214, v106
	v_mul_u32_u24_e32 v110, 0x214, v109
	v_mul_u32_u24_e32 v112, 0x214, v111
	v_mul_u32_u24_e32 v114, 0x214, v113
	v_lshl_or_b32 v117, v175, 6, v174
	v_mov_b32_e32 v69, v65
	v_add_u32_e32 v70, 0xf7c00000, v1
	s_lshl_b32 s3, s92, 17
	v_lshl_or_b32 v72, v174, 11, v68
	v_mov_b32_e32 v73, v65
	s_movk_i32 s33, 0x410
	v_lshlrev_b32_e32 v118, 2, v174
	s_mov_b32 s41, 0x41a00000
	s_mov_b32 s44, 0x3f2aaaab
	v_mov_b32_e32 v119, 0x3ecc95a3
	s_mov_b32 s45, 0x3f317218
	s_mov_b32 s46, 0x7f800000
	s_mov_b32 s47, 0x33800000
	s_mov_b64 s[14:15], 0x16600000
	s_mov_b64 s[16:17], 0x2000
	s_mov_b64 s[18:19], 0x4000
	s_mov_b64 s[20:21], 0x6000
	s_movk_i32 s48, 0x2000
	s_movk_i32 s49, 0x3000
	s_mov_b64 s[22:23], 0x16800000
	s_mov_b64 s[24:25], 0x9518000
	v_lshlrev_b32_e32 v74, 1, v0
	s_mov_b32 s50, 0x4301000
	v_lshlrev_b32_e32 v78, 1, v2
	s_mov_b64 s[26:27], 0x10600000
	v_lshlrev_b32_e32 v80, 1, v4
	s_mov_b64 s[28:29], 0x12600000
	v_lshlrev_b32_e32 v82, 1, v8
	v_lshlrev_b32_e32 v84, 1, v6
	s_mov_b64 s[30:31], 0x14600000
	v_mov_b32_e32 v86, 0x3f317218
	v_mov_b32_e32 v120, 0x7f800000
	v_mov_b32_e32 v121, 0x7fc00000
	v_mov_b32_e32 v122, 0xff800000
	s_mov_b32 s51, s2
	s_mov_b32 s54, s2
	s_lshl_b32 s55, s54, 8
	s_and_b32 s55, s55, 0xf00
	s_lshl_b32 s56, s54, 4
	s_and_b32 s56, s56, 0xfffff000
	s_or_b32 s55, s56, s55
	s_lshl_b32 s56, s54, 3
	s_and_b32 s56, s56, 0x780
	s_load_dwordx2 s[58:59], s[0:1], 0xb8
	s_waitcnt lgkmcnt(0)
	s_add_u32 s58, s58, s56
	s_addc_u32 s59, s59, 0
	s_add_u32 s58, s58, s50
	s_addc_u32 s59, s59, 0
	v_mov_b32_e32 v158, s58
	v_mov_b32_e32 v159, s59
	v_mov_b32_e32 v160, v74
	v_mov_b32_e32 v161, 0
	v_lshl_add_u64 v[158:159], v[158:159], 0, v[160:161]
	v_or_b32_e32 v160, s55, v76
	v_mad_i64_i32 v[162:163], s[60:61], v160, s49, v[158:159]
	global_load_dwordx4 v[142:145], v[162:163], off
	v_or_b32_e32 v160, s55, v100
	v_mad_i64_i32 v[162:163], s[60:61], v160, s49, v[158:159]
	global_load_dwordx4 v[146:149], v[162:163], off
	v_or_b32_e32 v160, s55, v102
	v_mad_i64_i32 v[162:163], s[60:61], v160, s49, v[158:159]
	global_load_dwordx4 v[150:153], v[162:163], off
	v_add_u32_e32 v160, s55, v104
	v_mad_i64_i32 v[162:163], s[60:61], v160, s49, v[158:159]
	global_load_dwordx4 v[154:157], v[162:163], off
	s_branch .LBB0_239

; __device__ __forceinline__ void vt_unit(const Params& p, int unit, bfu* tile  ) {
;     const int blk = unit & 15, bh = unit >> 4, h = bh & 15, b = bh >> 4, t0 = blk * 256, tid = threadIdx.x;
;     const bfu* proj = (const bfu*)(p.ws + WS_PROJ);
;     bfu* vt = (bfu*)(p.ws + WS_VT);
; #pragma unroll
;     for (int i = 0; i < 4; ++i) {
;         const int e = tid + 512 * i, t = e >> 3, d8 = (e & 7) * 8;
;         const uint4 v = *(const uint4*)(proj + (size_t)(b * 4096 + t0 + t) * NPROJ + 2048 + h * 64 + d8);
;         bfu* tp = tile + d8 * 266 + t;
;         tp[0] = (bfu)(v.x & 0xffff); tp[266] = (bfu)(v.x >> 16); tp[2 * 266] = (bfu)(v.y & 0xffff); tp[3 * 266] = (bfu)(v.y >> 16);
;         tp[4 * 266] = (bfu)(v.z & 0xffff); tp[5 * 266] = (bfu)(v.z >> 16); tp[6 * 266] = (bfu)(v.w & 0xffff); tp[7 * 266] = (bfu)(v.w >> 16);
;     }
;     __syncthreads();
.LBB0_278:
	s_load_dwordx2 s[34:35], s[0:1], 0xb8
	s_lshl_b32 s4, s51, 8
	s_and_b32 s36, s4, 0xf00
	s_lshl_b32 s4, s51, 4
	s_and_b32 s4, s4, 0xfffff000
	s_or_b32 s37, s4, s36
	v_or_b32_e32 v0, s37, v76
	s_waitcnt lgkmcnt(0)
	v_mov_b64_e32 v[12:13], s[34:35]
	s_lshl_b32 s4, s51, 3
	v_mad_i64_i32 v[0:1], s[38:39], v0, s49, v[12:13]
	s_and_b32 s4, s4, 0x780
	v_lshl_add_u64 v[0:1], v[0:1], 0, s[4:5]
	v_mov_b32_e32 v75, v65
	v_lshl_add_u64 v[0:1], v[0:1], 0, v[74:75]
	v_add_co_u32_e32 v0, vcc, s50, v0
	v_or_b32_e32 v4, s37, v100
	s_nop 0
	v_addc_co_u32_e32 v1, vcc, 0, v1, vcc
	v_mad_i64_i32 v[4:5], s[38:39], v4, s49, v[12:13]
	v_lshl_add_u64 v[4:5], v[4:5], 0, s[4:5]
	v_lshl_add_u64 v[4:5], v[4:5], 0, v[74:75]
	v_add_co_u32_e32 v4, vcc, s50, v4
	v_or_b32_e32 v8, s37, v102
	s_nop 0
	v_addc_co_u32_e32 v5, vcc, 0, v5, vcc
	v_mad_i64_i32 v[8:9], s[38:39], v8, s49, v[12:13]
	v_lshl_add_u64 v[8:9], v[8:9], 0, s[4:5]
	v_lshl_add_u64 v[8:9], v[8:9], 0, v[74:75]
	v_add_co_u32_e32 v8, vcc, s50, v8
	v_add_u32_e32 v14, s37, v104
	s_nop 0
	v_addc_co_u32_e32 v9, vcc, 0, v9, vcc
	v_mad_i64_i32 v[12:13], s[38:39], v14, s49, v[12:13]
	v_lshl_add_u64 v[12:13], v[12:13], 0, s[4:5]
	v_lshl_add_u64 v[12:13], v[12:13], 0, v[74:75]
	v_add_co_u32_e32 v12, vcc, s50, v12
	s_lshl_b32 s4, s51, 2
	s_nop 0
	v_addc_co_u32_e32 v13, vcc, 0, v13, vcc
	s_waitcnt vmcnt(0)
	v_mov_b64_e32 v[0:1], v[142:143]
	v_mov_b64_e32 v[2:3], v[144:145]
	v_mov_b64_e32 v[4:5], v[146:147]
	v_mov_b64_e32 v[6:7], v[148:149]
	v_mov_b64_e32 v[8:9], v[150:151]
	v_mov_b64_e32 v[10:11], v[152:153]
	v_mov_b64_e32 v[12:13], v[154:155]
	v_mov_b64_e32 v[14:15], v[156:157]
	s_andn2_b32 s4, s4, 63
	s_lshl_b32 s37, s36, 1
	s_add_u32 s38, s34, s37
	v_mov_b32_e32 v79, v65
	s_addc_u32 s39, s35, 0
	v_mov_b32_e32 v81, v65
	v_mov_b32_e32 v83, v65
	v_mov_b32_e32 v85, v65
	s_waitcnt vmcnt(3)
	ds_write_b16 v99, v0
	ds_write_b16_d16_hi v99, v0 offset:532
	ds_write_b16 v99, v1 offset:1064
	ds_write_b16_d16_hi v99, v1 offset:1596
	ds_write_b16 v99, v2 offset:2128
	ds_write_b16_d16_hi v99, v2 offset:2660
	ds_write_b16 v99, v3 offset:3192
	ds_write_b16_d16_hi v99, v3 offset:3724
	s_waitcnt vmcnt(2)
	ds_write_b16 v101, v4
	ds_write_b16_d16_hi v101, v4 offset:532
	ds_write_b16 v101, v5 offset:1064
	ds_write_b16_d16_hi v101, v5 offset:1596
	ds_write_b16 v101, v6 offset:2128
	ds_write_b16_d16_hi v101, v6 offset:2660
	ds_write_b16 v101, v7 offset:3192
	ds_write_b16_d16_hi v101, v7 offset:3724
	s_waitcnt vmcnt(1)
	ds_write_b16 v103, v8
	ds_write_b16_d16_hi v103, v8 offset:532
	ds_write_b16 v103, v9 offset:1064
	ds_write_b16_d16_hi v103, v9 offset:1596
	ds_write_b16 v103, v10 offset:2128
	ds_write_b16_d16_hi v103, v10 offset:2660
	ds_write_b16 v103, v11 offset:3192
	ds_write_b16_d16_hi v103, v11 offset:3724
	s_waitcnt vmcnt(0)
	ds_write_b16 v105, v12
	ds_write_b16_d16_hi v105, v12 offset:532
	ds_write_b16 v105, v13 offset:1064
	ds_write_b16_d16_hi v105, v13 offset:1596
	ds_write_b16 v105, v14 offset:2128
	ds_write_b16_d16_hi v105, v14 offset:2660
	ds_write_b16 v105, v15 offset:3192
	ds_write_b16_d16_hi v105, v15 offset:3724
	v_lshl_add_u64 v[0:1], s[38:39], 0, v[78:79]
	v_add_u32_e32 v2, v108, v107
	s_waitcnt lgkmcnt(0)
	s_barrier
	s_add_i32 s54, s51, s92
	s_cmpk_lt_i32 s54, 0x400
	s_cbranch_scc0 .Lp2_vt_nopf
	s_lshl_b32 s55, s54, 8
	s_and_b32 s55, s55, 0xf00
	s_lshl_b32 s56, s54, 4
	s_and_b32 s56, s56, 0xfffff000
	s_or_b32 s55, s56, s55
	s_lshl_b32 s56, s54, 3
	s_and_b32 s56, s56, 0x780
	s_load_dwordx2 s[58:59], s[0:1], 0xb8
	s_waitcnt lgkmcnt(0)
	s_add_u32 s58, s58, s56
	s_addc_u32 s59, s59, 0
	s_add_u32 s58, s58, s50
	s_addc_u32 s59, s59, 0
	v_mov_b32_e32 v158, s58
	v_mov_b32_e32 v159, s59
	v_mov_b32_e32 v160, v74
	v_mov_b32_e32 v161, 0
	v_lshl_add_u64 v[158:159], v[158:159], 0, v[160:161]
	v_or_b32_e32 v160, s55, v76
	v_mad_i64_i32 v[162:163], s[60:61], v160, s49, v[158:159]
	global_load_dwordx4 v[142:145], v[162:163], off
	v_or_b32_e32 v160, s55, v100
	v_mad_i64_i32 v[162:163], s[60:61], v160, s49, v[158:159]
	global_load_dwordx4 v[146:149], v[162:163], off
	v_or_b32_e32 v160, s55, v102
	v_mad_i64_i32 v[162:163], s[60:61], v160, s49, v[158:159]
	global_load_dwordx4 v[150:153], v[162:163], off
	v_add_u32_e32 v160, s55, v104
	v_mad_i64_i32 v[162:163], s[60:61], v160, s49, v[158:159]
	global_load_dwordx4 v[154:157], v[162:163], off
; __device__ __forceinline__ void vt_unit(const Params& p, int unit, bfu* tile  ) {
;     ...
; #pragma unroll
;     for (int br = 0; br < 3; ++br) {
;         const int dsh = 2 * br, dil = 1 << dsh, nch = (256 >> dsh) >> 3;
; #pragma unroll
;         for (int i = 0; i < 4; ++i) {
;             const int e = tid + 512 * i, d = e >> 5, rem = e & 31, ch = rem % nch, r = rem / nch;
;             const bfu* tp = tile + d * 266 + r + ((ch * 8) << dsh);
;             uint4 o;
;             o.x = (unsigned)tp[0] | ((unsigned)tp[dil] << 16); o.y = (unsigned)tp[2 * dil] | ((unsigned)tp[3 * dil] << 16);
;             o.z = (unsigned)tp[4 * dil] | ((unsigned)tp[5 * dil] << 16); o.w = (unsigned)tp[6 * dil] | ((unsigned)tp[7 * dil] << 16);
;             *(uint4*)(vt + (size_t)br * VT_SZ + ((size_t)(bh * 64 + d)) * 4096 + r * (4096 >> dsh) + (t0 >> dsh) + ch * 8) = o;
;         }
;     }
;     __syncthreads();
.Lp2_vt_nopf:
	v_lshl_add_u64 v[4:5], v[0:1], 0, s[26:27]
	ds_read2_b32 v[0:1], v2 offset1:1
	ds_read2_b32 v[2:3], v2 offset0:2 offset1:3
	v_or_b32_e32 v6, s4, v106
	v_ashrrev_i32_e32 v7, 31, v6
	v_lshlrev_b64 v[6:7], 13, v[6:7]
	v_lshl_add_u64 v[8:9], v[4:5], 0, v[6:7]
	s_waitcnt lgkmcnt(0)
	global_store_dwordx4 v[8:9], v[0:3], off
	v_or_b32_e32 v8, s4, v109
	v_ashrrev_i32_e32 v9, 31, v8
	v_add_u32_e32 v2, v108, v110
	ds_read2_b32 v[0:1], v2 offset1:1
	ds_read2_b32 v[2:3], v2 offset0:2 offset1:3
	v_lshlrev_b64 v[8:9], 13, v[8:9]
	v_lshl_add_u64 v[10:11], v[4:5], 0, v[8:9]
	s_waitcnt lgkmcnt(0)
	global_store_dwordx4 v[10:11], v[0:3], off
	s_nop 1
	v_add_u32_e32 v2, v108, v112
	ds_read2_b32 v[0:1], v2 offset1:1
	ds_read2_b32 v[2:3], v2 offset0:2 offset1:3
	v_or_b32_e32 v10, s4, v111
	v_ashrrev_i32_e32 v11, 31, v10
	v_lshlrev_b64 v[10:11], 13, v[10:11]
	v_lshl_add_u64 v[12:13], v[4:5], 0, v[10:11]
	s_waitcnt lgkmcnt(0)
	global_store_dwordx4 v[12:13], v[0:3], off
	v_add_u32_e32 v12, s4, v113
	v_ashrrev_i32_e32 v13, 31, v12
	v_add_u32_e32 v2, v108, v114
	ds_read2_b32 v[0:1], v2 offset1:1
	ds_read2_b32 v[2:3], v2 offset0:2 offset1:3
	v_lshlrev_b64 v[12:13], 13, v[12:13]
	v_lshl_add_u64 v[4:5], v[4:5], 0, v[12:13]
	s_lshr_b32 s4, s36, 1
	s_waitcnt lgkmcnt(0)
	global_store_dwordx4 v[4:5], v[0:3], off
	s_nop 1
	v_add_u32_e32 v2, v115, v107
	ds_read_u16 v3, v2
	ds_read_u16 v14, v2 offset:8
	ds_read_u16 v15, v2 offset:16
	ds_read_u16 v16, v2 offset:24
	ds_read_u16 v17, v2 offset:32
	ds_read_u16 v18, v2 offset:40
	ds_read_u16 v19, v2 offset:48
	ds_read_u16 v20, v2 offset:56
	v_lshl_add_u64 v[0:1], s[34:35], 0, v[80:81]
	v_lshl_add_u64 v[0:1], v[0:1], 0, s[4:5]
	v_lshl_add_u64 v[0:1], v[0:1], 0, v[74:75]
	v_lshl_add_u64 v[4:5], v[0:1], 0, s[28:29]
	s_waitcnt lgkmcnt(4)
	v_lshl_or_b32 v1, v16, 16, v15
	v_add_u32_e32 v16, v115, v110
	v_lshl_or_b32 v0, v14, 16, v3
	s_waitcnt lgkmcnt(2)
	v_lshl_or_b32 v2, v18, 16, v17
	s_waitcnt lgkmcnt(0)
	v_lshl_or_b32 v3, v20, 16, v19
	ds_read_u16 v17, v16
	ds_read_u16 v18, v16 offset:8
	ds_read_u16 v19, v16 offset:16
	ds_read_u16 v20, v16 offset:24
	ds_read_u16 v21, v16 offset:32
	ds_read_u16 v22, v16 offset:40
	ds_read_u16 v23, v16 offset:48
	ds_read_u16 v16, v16 offset:56
	v_lshl_add_u64 v[14:15], v[4:5], 0, v[6:7]
	global_store_dwordx4 v[14:15], v[0:3], off
	v_lshl_add_u64 v[14:15], v[4:5], 0, v[8:9]
	s_lshr_b32 s4, s36, 3
	s_waitcnt lgkmcnt(0)
	v_lshl_or_b32 v3, v16, 16, v23
	v_add_u32_e32 v16, v115, v112
	v_lshl_or_b32 v0, v18, 16, v17
	v_lshl_or_b32 v1, v20, 16, v19
	v_lshl_or_b32 v2, v22, 16, v21
	ds_read_u16 v17, v16
	ds_read_u16 v18, v16 offset:8
	ds_read_u16 v19, v16 offset:16
	ds_read_u16 v20, v16 offset:24
	ds_read_u16 v21, v16 offset:32
	ds_read_u16 v22, v16 offset:40
	ds_read_u16 v23, v16 offset:48
	ds_read_u16 v16, v16 offset:56
	global_store_dwordx4 v[14:15], v[0:3], off
	v_lshl_add_u64 v[14:15], v[4:5], 0, v[10:11]
	v_lshl_add_u64 v[4:5], v[4:5], 0, v[12:13]
	s_waitcnt lgkmcnt(6)
	v_lshl_or_b32 v0, v18, 16, v17
	s_waitcnt lgkmcnt(0)
	v_lshl_or_b32 v3, v16, 16, v23
	v_add_u32_e32 v16, v115, v114
	v_lshl_or_b32 v1, v20, 16, v19
	v_lshl_or_b32 v2, v22, 16, v21
	ds_read_u16 v17, v16
	ds_read_u16 v18, v16 offset:8
	ds_read_u16 v19, v16 offset:16
	ds_read_u16 v20, v16 offset:24
	ds_read_u16 v21, v16 offset:32
	ds_read_u16 v22, v16 offset:40
	ds_read_u16 v23, v16 offset:48
	ds_read_u16 v16, v16 offset:56
	global_store_dwordx4 v[14:15], v[0:3], off
	s_waitcnt lgkmcnt(6)
	s_nop 0
	v_lshl_or_b32 v0, v18, 16, v17
	s_waitcnt lgkmcnt(4)
	v_lshl_or_b32 v1, v20, 16, v19
	s_waitcnt lgkmcnt(2)
	v_lshl_or_b32 v2, v22, 16, v21
	s_waitcnt lgkmcnt(0)
	v_lshl_or_b32 v3, v16, 16, v23
	global_store_dwordx4 v[4:5], v[0:3], off
	s_nop 1
	v_add_u32_e32 v2, v116, v107
	ds_read_u16 v3, v2
	ds_read_u16 v14, v2 offset:32
	ds_read_u16 v15, v2 offset:64
	ds_read_u16 v16, v2 offset:96
	ds_read_u16 v17, v2 offset:128
	ds_read_u16 v18, v2 offset:160
	ds_read_u16 v19, v2 offset:192
	ds_read_u16 v20, v2 offset:224
	v_lshl_add_u64 v[0:1], s[34:35], 0, v[82:83]
	v_lshl_add_u64 v[0:1], v[0:1], 0, s[4:5]
	v_lshl_add_u64 v[0:1], v[0:1], 0, v[84:85]
	v_lshl_add_u64 v[4:5], v[0:1], 0, s[30:31]
	s_waitcnt lgkmcnt(6)
	v_lshl_or_b32 v0, v14, 16, v3
	v_add_u32_e32 v14, v116, v110
	s_waitcnt lgkmcnt(4)
	v_lshl_or_b32 v1, v16, 16, v15
	s_waitcnt lgkmcnt(2)
	v_lshl_or_b32 v2, v18, 16, v17
	s_waitcnt lgkmcnt(0)
	v_lshl_or_b32 v3, v20, 16, v19
	ds_read_u16 v15, v14
	ds_read_u16 v16, v14 offset:32
	ds_read_u16 v17, v14 offset:64
	ds_read_u16 v18, v14 offset:96
	ds_read_u16 v19, v14 offset:128
	ds_read_u16 v20, v14 offset:160
	ds_read_u16 v21, v14 offset:192
	ds_read_u16 v14, v14 offset:224
	v_lshl_add_u64 v[6:7], v[4:5], 0, v[6:7]
	global_store_dwordx4 v[6:7], v[0:3], off
	v_lshl_add_u64 v[6:7], v[4:5], 0, v[8:9]
	v_add_u32_e32 v8, v116, v112
	s_waitcnt lgkmcnt(6)
	v_lshl_or_b32 v0, v16, 16, v15
	s_waitcnt lgkmcnt(4)
	v_lshl_or_b32 v1, v18, 16, v17
	s_waitcnt lgkmcnt(2)
	v_lshl_or_b32 v2, v20, 16, v19
	s_waitcnt lgkmcnt(0)
	v_lshl_or_b32 v3, v14, 16, v21
	ds_read_u16 v9, v8
	ds_read_u16 v14, v8 offset:32
	ds_read_u16 v15, v8 offset:64
	ds_read_u16 v16, v8 offset:96
	ds_read_u16 v17, v8 offset:128
	ds_read_u16 v18, v8 offset:160
	ds_read_u16 v19, v8 offset:192
	ds_read_u16 v8, v8 offset:224
	global_store_dwordx4 v[6:7], v[0:3], off
	v_lshl_add_u64 v[6:7], v[4:5], 0, v[10:11]
	v_lshl_add_u64 v[4:5], v[4:5], 0, v[12:13]
	s_waitcnt lgkmcnt(6)
	v_lshl_or_b32 v0, v14, 16, v9
	s_waitcnt lgkmcnt(0)
	v_lshl_or_b32 v3, v8, 16, v19
	v_add_u32_e32 v8, v116, v114
	v_lshl_or_b32 v1, v16, 16, v15
	v_lshl_or_b32 v2, v18, 16, v17
	ds_read_u16 v9, v8
	ds_read_u16 v10, v8 offset:32
	ds_read_u16 v11, v8 offset:64
	ds_read_u16 v14, v8 offset:96
	ds_read_u16 v15, v8 offset:128
	ds_read_u16 v16, v8 offset:160
	ds_read_u16 v17, v8 offset:192
	ds_read_u16 v8, v8 offset:224
	global_store_dwordx4 v[6:7], v[0:3], off
	s_waitcnt lgkmcnt(6)
	s_nop 0
	v_lshl_or_b32 v0, v10, 16, v9
	s_waitcnt lgkmcnt(4)
	v_lshl_or_b32 v1, v14, 16, v11
	s_waitcnt lgkmcnt(2)
	v_lshl_or_b32 v2, v16, 16, v15
	s_waitcnt lgkmcnt(0)
	v_lshl_or_b32 v3, v8, 16, v17
	global_store_dwordx4 v[4:5], v[0:3], off
	s_barrier
	s_branch .LBB0_238
